# stick-breaking tile loop: removed the dead denormal/infinity guards of logf(1+e), e in [0,1] (6 of 19 VALU ops per score, bit-identical)
# speedup vs baseline: 1.0076x; 1.0076x over previous
.LBB0_465:
	s_cmp_ge_i32 s23, s4
	s_cselect_b64 s[16:17], -1, 0
	s_or_b64 s[16:17], s[16:17], s[14:15]
	s_and_b64 vcc, exec, s[16:17]
	s_cbranch_vccnz .LBB0_467
	v_add3_u32 v130, s18, v192, v205
	ds_read_b128 v[64:67], v130 offset:8704
	ds_read_b128 v[132:135], v130 offset:8736
	v_or_b32_e32 v163, s23, v200
	v_add3_u32 v207, s22, v204, v206
	s_waitcnt lgkmcnt(1)
	v_mfma_f32_32x32x16_bf16 v[66:81], v[64:67], v[82:85], 0
	s_waitcnt lgkmcnt(0)
	v_mfma_f32_32x32x16_bf16 v[66:81], v[132:135], v[86:89], v[66:81]
	ds_read_b128 v[132:135], v130 offset:8768
	ds_read_b128 v[136:139], v130 offset:8800
	s_waitcnt lgkmcnt(1)
	v_mfma_f32_32x32x16_bf16 v[66:81], v[132:135], v[90:93], v[66:81]
	s_waitcnt lgkmcnt(0)
	v_mfma_f32_32x32x16_bf16 v[66:81], v[136:139], v[94:97], v[66:81]
	ds_read_b128 v[132:135], v130 offset:8832
	ds_read_b128 v[136:139], v130 offset:8864
	s_waitcnt lgkmcnt(1)
	v_mfma_f32_32x32x16_bf16 v[66:81], v[132:135], v[98:101], v[66:81]
	s_waitcnt lgkmcnt(0)
	v_mfma_f32_32x32x16_bf16 v[66:81], v[136:139], v[102:105], v[66:81]
	ds_read_b128 v[132:135], v130 offset:8896
	ds_read_b128 v[136:139], v130 offset:8928
	ds_read_b128 v[208:211], v130 offset:224
	s_waitcnt lgkmcnt(2)
	v_mfma_f32_32x32x16_bf16 v[66:81], v[132:135], v[106:109], v[66:81]
	s_waitcnt lgkmcnt(1)
	v_mfma_f32_32x32x16_bf16 v[66:81], v[136:139], v[110:113], v[66:81]
	s_nop 11
	v_mov_b32_e32 v64, v66
	v_mov_b32_e32 v65, v68
	v_mov_b32_e32 v68, v67
	v_pk_mul_f32 v[132:133], v[64:65], s[68:69] op_sel_hi:[1,0]
	v_mov_b32_e32 v66, v70
	v_pk_mul_f32 v[134:135], v[68:69], s[68:69] op_sel_hi:[1,0]
	v_mul_f32_e64 v70, |v132|, s54
	v_mov_b32_e32 v67, v72
	v_mul_f32_e64 v72, |v134|, s54
	v_exp_f32_e32 v70, v70
	v_mul_f32_e64 v131, |v133|, s54
	v_exp_f32_e32 v72, v72
	v_mul_f32_e64 v138, |v135|, s54
	v_exp_f32_e32 v131, v131
	v_pk_mul_f32 v[136:137], v[66:67], s[68:69] op_sel_hi:[1,0]
	v_exp_f32_e32 v138, v138
	v_mul_f32_e64 v139, |v136|, s54
	v_add_f32_e32 v70, 1.0, v70
	v_exp_f32_e32 v139, v139
	v_add_f32_e32 v72, 1.0, v72
	v_add_f32_e32 v131, 1.0, v131
	v_add_f32_e32 v138, 1.0, v138
	v_log_f32_e32 v70, v70
	v_add_f32_e32 v139, 1.0, v139
	v_log_f32_e32 v72, v72
	v_log_f32_e32 v131, v131
	v_log_f32_e32 v138, v138
	v_mov_b32_e32 v142, v139
	v_mul_f32_e32 v139, 0x3f317217, v70
	v_mul_f32_e32 v140, 0x3f317217, v72
	v_fma_f32 v139, v70, s86, -v139
	v_mul_f32_e32 v141, 0x3f317217, v131
	v_fma_f32 v140, v72, s86, -v140
	v_fmac_f32_e32 v139, 0x3377d1cf, v70
	v_mul_f32_e32 v143, 0x3f317217, v138
	v_fma_f32 v141, v131, s86, -v141
	v_fmac_f32_e32 v140, 0x3377d1cf, v72
	v_fmac_f32_e32 v139, 0x3f317217, v70
	v_fma_f32 v143, v138, s86, -v143
	v_fmac_f32_e32 v141, 0x3377d1cf, v131
	v_fmac_f32_e32 v140, 0x3f317217, v72
	v_fmac_f32_e32 v143, 0x3377d1cf, v138
	v_fmac_f32_e32 v141, 0x3f317217, v131
	v_fmac_f32_e32 v143, 0x3f317217, v138
	v_mov_b32_e32 v131, v141
	v_min_f32_e32 v132, 0, v132
	v_min_f32_e32 v133, 0, v133
	v_mov_b32_e32 v138, v139
	v_mov_b32_e32 v139, v131
	v_pk_add_f32 v[166:167], v[132:133], v[138:139] neg_lo:[0,1] neg_hi:[0,1]
	v_pk_fma_f32 v[174:175], v[64:65], s[68:69], v[166:167] op_sel_hi:[1,0,1] neg_lo:[1,0,0] neg_hi:[1,0,0]
	v_log_f32_e32 v65, v142
	v_min_f32_e32 v134, 0, v134
	v_min_f32_e32 v135, 0, v135
	v_mov_b32_e32 v141, v143
	v_pk_add_f32 v[164:165], v[134:135], v[140:141] neg_lo:[0,1] neg_hi:[0,1]
	v_mov_b32_e32 v72, v71
	v_pk_fma_f32 v[172:173], v[68:69], s[68:69], v[164:165] op_sel_hi:[1,0,1] neg_lo:[1,0,0] neg_hi:[1,0,0]
	v_mul_f32_e32 v68, 0x3f317217, v65
	v_fma_f32 v70, v65, s86, -v68
	v_pk_mul_f32 v[68:69], v[72:73], s[68:69] op_sel_hi:[1,0]
	v_fmac_f32_e32 v70, 0x3377d1cf, v65
	v_mul_f32_e64 v71, |v68|, s54
	v_exp_f32_e32 v71, v71
	v_fmac_f32_e32 v70, 0x3f317217, v65
	v_mul_f32_e64 v131, |v137|, s54
	v_exp_f32_e32 v131, v131
	v_mov_b32_e32 v65, v70
	v_add_f32_e32 v70, 1.0, v71
	v_mul_f32_e64 v133, |v69|, s54
	v_exp_f32_e32 v133, v133
	v_log_f32_e32 v71, v70
	v_mov_b32_e32 v70, v65
	v_min_f32_e32 v64, 0, v136
	v_mul_f32_e32 v65, 0x3f317217, v71
	v_fma_f32 v65, v71, s86, -v65
	v_fmac_f32_e32 v65, 0x3377d1cf, v71
	v_fmac_f32_e32 v65, 0x3f317217, v71
	v_min_f32_e32 v68, 0, v68
	v_min_f32_e32 v69, 0, v69
	v_add_f32_e32 v71, 1.0, v131
	v_mov_b32_e32 v140, v78
	v_mov_b32_e32 v141, v80
	v_log_f32_e32 v71, v71
	v_mov_b32_e32 v132, v65
	v_min_f32_e32 v65, 0, v137
	v_mul_f32_e32 v131, 0x3f317217, v71
	v_fma_f32 v131, v71, s86, -v131
	v_fmac_f32_e32 v131, 0x3377d1cf, v71
	v_fmac_f32_e32 v131, 0x3f317217, v71
	v_pk_mul_f32 v[142:143], v[140:141], s[68:69] op_sel_hi:[1,0]
	v_mov_b32_e32 v80, v79
	v_mov_b32_e32 v71, v131
	v_mov_b32_e32 v71, v71
	v_add_f32_e32 v131, 1.0, v133
	v_pk_add_f32 v[168:169], v[64:65], v[70:71] neg_lo:[0,1] neg_hi:[0,1]
	v_mov_b32_e32 v65, v76
	v_log_f32_e32 v131, v131
	v_pk_fma_f32 v[176:177], v[66:67], s[68:69], v[168:169] op_sel_hi:[1,0,1] neg_lo:[1,0,0] neg_hi:[1,0,0]
	v_mov_b32_e32 v76, v75
	v_pk_mul_f32 v[144:145], v[80:81], s[68:69] op_sel_hi:[1,0]
	v_mul_f32_e32 v64, 0x3f317217, v131
	v_fma_f32 v70, v131, s86, -v64
	v_mov_b32_e32 v64, v74
	v_pk_mul_f32 v[66:67], v[64:65], s[68:69] op_sel_hi:[1,0]
	v_fmac_f32_e32 v70, 0x3377d1cf, v131
	v_mul_f32_e64 v71, |v66|, s54
	v_exp_f32_e32 v71, v71
	v_fmac_f32_e32 v70, 0x3f317217, v131
	v_min_f32_e32 v66, 0, v66
	v_mov_b32_e32 v133, v70
	v_add_f32_e32 v70, 1.0, v71
	v_pk_add_f32 v[170:171], v[68:69], v[132:133] neg_lo:[0,1] neg_hi:[0,1]
	ds_read_b128 v[132:135], v130 offset:32
	v_log_f32_e32 v70, v70
	v_pk_fma_f32 v[178:179], v[72:73], s[68:69], v[170:171] op_sel_hi:[1,0,1] neg_lo:[1,0,0] neg_hi:[1,0,0]
	v_mul_f32_e64 v73, |v67|, s54
	v_exp_f32_e32 v73, v73
	v_mul_f32_e32 v68, 0x3f317217, v70
	v_fma_f32 v71, v70, s86, -v68
	v_pk_mul_f32 v[68:69], v[76:77], s[68:69] op_sel_hi:[1,0]
	v_fmac_f32_e32 v71, 0x3377d1cf, v70
	v_mul_f32_e64 v72, |v68|, s54
	v_exp_f32_e32 v72, v72
	v_fmac_f32_e32 v71, 0x3f317217, v70
	v_mul_f32_e64 v74, |v69|, s54
	v_exp_f32_e32 v74, v74
	v_mov_b32_e32 v70, v71
	v_add_f32_e32 v71, 1.0, v72
	v_min_f32_e32 v67, 0, v67
	v_min_f32_e32 v68, 0, v68
	v_log_f32_e32 v71, v71
	v_mov_b32_e32 v70, v70
	v_min_f32_e32 v69, 0, v69
	v_mul_f32_e32 v72, 0x3f317217, v71
	v_fma_f32 v72, v71, s86, -v72
	v_fmac_f32_e32 v72, 0x3377d1cf, v71
	v_fmac_f32_e32 v72, 0x3f317217, v71
	s_nop 1
	v_mov_b32_e32 v71, v72
	v_add_f32_e32 v72, 1.0, v73
	s_nop 1
	v_log_f32_e32 v73, v72
	v_mov_b32_e32 v72, v71
	v_mul_f32_e32 v71, 0x3f317217, v73
	v_fma_f32 v71, v73, s86, -v71
	v_fmac_f32_e32 v71, 0x3377d1cf, v73
	v_fmac_f32_e32 v71, 0x3f317217, v73
	s_nop 1
	v_add_f32_e32 v73, 1.0, v74
	v_pk_add_f32 v[180:181], v[66:67], v[70:71] neg_lo:[0,1] neg_hi:[0,1]
	v_mul_f32_e64 v70, |v143|, s54
	v_log_f32_e32 v73, v73
	v_pk_fma_f32 v[184:185], v[64:65], s[68:69], v[180:181] op_sel_hi:[1,0,1] neg_lo:[1,0,0] neg_hi:[1,0,0]
	v_mul_f32_e64 v65, |v142|, s54
	v_exp_f32_e32 v65, v65
	v_mul_f32_e32 v64, 0x3f317217, v73
	v_fma_f32 v64, v73, s86, -v64
	v_fmac_f32_e32 v64, 0x3377d1cf, v73
	v_fmac_f32_e32 v64, 0x3f317217, v73
	v_exp_f32_e32 v131, v70
	v_mov_b32_e32 v73, v64
	v_add_f32_e32 v64, 1.0, v65
	v_mul_f32_e64 v66, |v144|, s54
	v_exp_f32_e32 v66, v66
	v_log_f32_e32 v64, v64
	v_pk_add_f32 v[182:183], v[68:69], v[72:73] neg_lo:[0,1] neg_hi:[0,1]
	v_add_f32_e32 v131, 1.0, v131
	v_pk_fma_f32 v[186:187], v[76:77], s[68:69], v[182:183] op_sel_hi:[1,0,1] neg_lo:[1,0,0] neg_hi:[1,0,0]
	v_mul_f32_e32 v65, 0x3f317217, v64
	v_fma_f32 v65, v64, s86, -v65
	v_fmac_f32_e32 v65, 0x3377d1cf, v64
	v_fmac_f32_e32 v65, 0x3f317217, v64
	v_min_f32_e32 v142, 0, v142
	v_min_f32_e32 v143, 0, v143
	v_mov_b32_e32 v64, v65
	v_add_f32_e32 v65, 1.0, v66
	v_min_f32_e32 v144, 0, v144
	v_mov_b32_e32 v247, v180
	v_log_f32_e32 v68, v65
	v_mov_b32_e32 v146, v64
	ds_read_b128 v[64:67], v130
	v_mul_f32_e32 v69, 0x3f317217, v68
	v_fma_f32 v69, v68, s86, -v69
	v_fmac_f32_e32 v69, 0x3377d1cf, v68
	v_fmac_f32_e32 v69, 0x3f317217, v68
	s_nop 0
	v_mov_b32_e32 v147, v69
	s_waitcnt lgkmcnt(0)
	v_mfma_f32_32x32x16_bf16 v[64:79], v[64:67], v[82:85], 0
	v_mov_b32_e32 v148, v147
	s_nop 0
	ds_read_b128 v[136:139], v130 offset:64
	v_log_f32_e32 v131, v131
	v_mfma_f32_32x32x16_bf16 v[64:79], v[132:135], v[86:89], v[64:79]
	v_mul_f32_e32 v132, 0x3f317217, v131
	v_fma_f32 v147, v131, s86, -v132
	ds_read_b128 v[132:135], v130 offset:96
	v_fmac_f32_e32 v147, 0x3377d1cf, v131
	v_fmac_f32_e32 v147, 0x3f317217, v131
	s_waitcnt lgkmcnt(1)
	v_mfma_f32_32x32x16_bf16 v[64:79], v[136:139], v[90:93], v[64:79]
	v_mul_f32_e64 v137, |v145|, s54
	v_exp_f32_e32 v149, v137
	ds_read_b128 v[136:139], v130 offset:128
	s_waitcnt lgkmcnt(1)
	v_mfma_f32_32x32x16_bf16 v[64:79], v[132:135], v[94:97], v[64:79]
	v_add_f32_e32 v131, 1.0, v149
	v_add_f32_e64 v188, v142, -v146
	v_add_f32_e64 v189, v143, -v147
	v_min_f32_e32 v145, 0, v145
	ds_read_b128 v[132:135], v130 offset:160
	s_waitcnt lgkmcnt(1)
	v_mfma_f32_32x32x16_bf16 v[64:79], v[136:139], v[98:101], v[64:79]
	v_log_f32_e32 v131, v131
	v_pk_fma_f32 v[212:213], v[140:141], s[68:69], v[188:189] op_sel_hi:[1,0,1] neg_lo:[1,0,0] neg_hi:[1,0,0]
	v_mul_f32_e32 v136, 0x3f317217, v131
	v_fma_f32 v140, v131, s86, -v136
	ds_read_b128 v[136:139], v130 offset:192
	s_waitcnt lgkmcnt(1)
	v_mfma_f32_32x32x16_bf16 v[64:79], v[132:135], v[102:105], v[64:79]
	v_fmac_f32_e32 v140, 0x3377d1cf, v131
	v_fmac_f32_e32 v140, 0x3f317217, v131
	s_nop 0
	v_mov_b32_e32 v149, v140
	s_waitcnt lgkmcnt(0)
	v_mfma_f32_32x32x16_bf16 v[64:79], v[136:139], v[106:109], v[64:79]
	v_add_f32_e64 v190, v144, -v148
	v_add_f32_e64 v191, v145, -v149
	ds_read_b64_tr_b16 v[146:147], v207 offset:45056
	ds_read_b64_tr_b16 v[142:143], v207 offset:45120
	ds_read_b64_tr_b16 v[138:139], v207 offset:45184
	ds_read_b64_tr_b16 v[134:135], v207 offset:45248
	ds_read_b64_tr_b16 v[148:149], v207 offset:47616
	ds_read_b64_tr_b16 v[144:145], v207 offset:47680
	ds_read_b64_tr_b16 v[140:141], v207 offset:47744
	ds_read_b64_tr_b16 v[136:137], v207 offset:47808
	ds_read_b64_tr_b16 v[130:131], v207 offset:50176
	ds_read_b64_tr_b16 v[132:133], v207 offset:52736
	v_pk_fma_f32 v[216:217], v[80:81], s[68:69], v[190:191] op_sel_hi:[1,0,1] neg_lo:[1,0,0] neg_hi:[1,0,0]
	v_or_b32_e32 v80, 34, v163
	v_cmp_lt_i32_e64 s[26:27], v80, v153
	v_mfma_f32_32x32x16_bf16 v[64:79], v[208:211], v[110:113], v[64:79]
	v_or_b32_e32 v208, 32, v163
	v_cmp_lt_i32_e64 s[30:31], v208, v152
	v_or_b32_e32 v208, 33, v163
	v_cmp_lt_i32_e64 s[40:41], v208, v152
	v_cndmask_b32_e64 v80, 0, v174, s[30:31]
	v_or_b32_e32 v174, 35, v163
	v_cmp_lt_i32_e64 s[38:39], v174, v153
	v_cndmask_b32_e64 v81, 0, v175, s[26:27]
	v_cndmask_b32_e64 v174, 0, v172, s[40:41]
	v_cndmask_b32_e64 v175, 0, v173, s[38:39]
	v_pk_add_f32 v[80:81], v[80:81], v[174:175]
	v_or_b32_e32 v208, 40, v163
	v_pk_add_f32 v[172:173], v[80:81], v[80:81] op_sel:[0,1] op_sel_hi:[1,0]
	v_cmp_lt_i32_e64 s[22:23], v208, v152
	v_or_b32_e32 v173, 42, v163
	v_cmp_lt_i32_e64 s[18:19], v173, v153
	v_or_b32_e32 v173, 43, v163
	v_or_b32_e32 v208, 41, v163
	v_cmp_lt_i32_e64 s[28:29], v173, v153
	v_or_b32_e32 v173, 50, v163
	v_cmp_lt_i32_e64 s[34:35], v208, v152
	v_or_b32_e32 v208, 48, v163
	v_cmp_lt_i32_e32 vcc, v173, v153
	v_or_b32_e32 v173, 51, v163
	v_cmp_lt_i32_e64 s[42:43], v208, v152
	v_or_b32_e32 v208, 49, v163
	v_cmp_lt_i32_e64 s[16:17], v173, v153
	v_or_b32_e32 v173, 58, v163
	v_cmp_lt_i32_e64 s[44:45], v208, v152
	v_or_b32_e32 v208, 56, v163
	v_cmp_lt_i32_e64 s[14:15], v173, v153
	v_or_b32_e32 v173, 59, v163
	v_or_b32_e32 v210, 57, v163
	v_cmp_lt_i32_e64 s[36:37], v208, v152
	v_cmp_lt_i32_e64 s[20:21], v173, v153
	v_cmp_lt_i32_e64 s[24:25], v210, v152
	v_cndmask_b32_e32 v185, 0, v185, vcc
	v_cndmask_b32_e64 v184, 0, v184, s[42:43]
	v_cndmask_b32_e64 v187, 0, v187, s[16:17]
	v_cndmask_b32_e64 v186, 0, v186, s[44:45]
	v_cndmask_b32_e64 v209, 0, v213, s[14:15]
	v_cndmask_b32_e64 v208, 0, v212, s[36:37]
	v_cndmask_b32_e64 v211, 0, v217, s[20:21]
	v_cndmask_b32_e64 v210, 0, v216, s[24:25]
	v_pk_add_f32 v[184:185], v[184:185], v[186:187]
	v_pk_add_f32 v[208:209], v[208:209], v[210:211]
	v_pk_add_f32 v[240:241], v[184:185], v[184:185] op_sel:[0,1] op_sel_hi:[1,0]
	v_pk_add_f32 v[212:213], v[208:209], v[208:209] op_sel:[0,1] op_sel_hi:[1,0]
	ds_bpermute_b32 v216, v235, v212
	ds_bpermute_b32 v184, v235, v240
	v_mov_b32_e32 v246, v186
	v_mov_b32_e32 v244, v185
	v_cndmask_b32_e64 v177, 0, v177, s[18:19]
	s_waitcnt lgkmcnt(1)
	v_add_f32_e32 v208, v212, v216
	s_waitcnt lgkmcnt(0)
	v_cndmask_b32_e64 v213, 0, v184, s[10:11]
	v_add_f32_e32 v208, v213, v208
	v_add_f32_e32 v245, v162, v208
	v_pk_add_f32 v[246:247], v[246:247], v[244:245]
	v_add_f32_e32 v182, v182, v245
	v_add_f32_e32 v180, v246, v247
	v_mul_f32_e32 v180, 0x3fb8aa3b, v180
	v_exp_f32_e32 v180, v180
	v_add_f32_e32 v182, v185, v182
	v_mul_f32_e32 v182, 0x3fb8aa3b, v182
	v_cndmask_b32_e64 v176, 0, v176, s[22:23]
	v_cndmask_b32_e64 v179, 0, v179, s[28:29]
	v_cndmask_b32_e64 v178, 0, v178, s[34:35]
	v_exp_f32_e32 v182, v182
	v_pk_add_f32 v[176:177], v[176:177], v[178:179]
	v_cndmask_b32_e64 v213, 0, v180, s[42:43]
	v_add_f32_e32 v180, v181, v245
	v_pk_add_f32 v[242:243], v[176:177], v[176:177] op_sel:[0,1] op_sel_hi:[1,0]
	v_add_f32_e32 v180, v187, v180
	ds_bpermute_b32 v80, v235, v172
	ds_bpermute_b32 v176, v235, v242
	v_mul_f32_e32 v180, 0x3fb8aa3b, v180
	v_mov_b32_e32 v185, v240
	v_mov_b32_e32 v217, v212
	v_cndmask_b32_e64 v215, 0, v182, s[44:45]
	v_exp_f32_e32 v239, v180
	v_add_f32_e32 v180, v183, v245
	v_pk_add_f32 v[182:183], v[184:185], v[216:217]
	v_add_f32_e32 v180, 0, v180
	v_add_f32_e32 v181, v242, v183
	v_add_f32_e32 v181, v181, v216
	v_add_f32_e32 v181, v181, v184
	v_cndmask_b32_e64 v173, 0, v216, s[10:11]
	s_waitcnt lgkmcnt(1)
	v_cndmask_b32_e64 v208, 0, v80, s[10:11]
	v_mul_f32_e32 v180, 0x3fb8aa3b, v180
	s_waitcnt lgkmcnt(0)
	v_add_f32_e32 v181, v181, v176
	v_exp_f32_e32 v241, v180
	v_add_f32_e32 v180, v162, v173
	v_add_f32_e32 v173, v183, v216
	v_add_f32_e32 v181, v208, v181
	v_cndmask_b32_e64 v186, 0, v176, s[10:11]
	v_add_f32_e32 v173, v173, v184
	v_add_f32_e32 v185, v162, v181
	v_add_f32_e32 v173, v186, v173
	v_mov_b32_e32 v186, v174
	v_mov_b32_e32 v187, v166
	v_mov_b32_e32 v184, v81
	v_add_f32_e32 v164, v164, v185
	v_pk_add_f32 v[186:187], v[186:187], v[184:185]
	v_add_f32_e32 v81, v81, v164
	v_add_f32_e32 v164, v167, v185
	v_add_f32_e32 v165, v165, v185
	v_add_f32_e32 v166, v186, v187
	v_add_f32_e32 v164, v175, v164
	v_add_f32_e32 v165, 0, v165
	v_mul_f32_e32 v166, 0x3fb8aa3b, v166
	v_mul_f32_e32 v164, 0x3fb8aa3b, v164
	v_mul_f32_e32 v165, 0x3fb8aa3b, v165
	v_exp_f32_e32 v166, v166
	v_exp_f32_e32 v164, v164
	v_exp_f32_e32 v165, v165
	v_mov_b32_e32 v167, v168
	v_cndmask_b32_e64 v174, 0, v166, s[30:31]
	v_cndmask_b32_e64 v175, 0, v164, s[26:27]
	v_cndmask_b32_e64 v181, 0, v165, s[38:39]
	v_add_f32_e32 v165, v162, v173
	v_mov_b32_e32 v166, v178
	v_mov_b32_e32 v164, v177
	v_pk_add_f32 v[166:167], v[166:167], v[164:165]
	v_mul_f32_e32 v81, 0x3fb8aa3b, v81
	v_add_f32_e32 v164, v166, v167
	v_add_f32_e32 v166, v170, v165
	v_add_f32_e32 v167, v169, v165
	v_add_f32_e32 v165, v171, v165
	v_add_f32_e32 v166, v177, v166
	v_add_f32_e32 v167, v179, v167
	v_add_f32_e32 v165, 0, v165
	v_mul_f32_e32 v164, 0x3fb8aa3b, v164
	v_mul_f32_e32 v166, 0x3fb8aa3b, v166
	v_mul_f32_e32 v167, 0x3fb8aa3b, v167
	v_mul_f32_e32 v165, 0x3fb8aa3b, v165
	v_exp_f32_e32 v81, v81
	v_exp_f32_e32 v164, v164
	v_exp_f32_e32 v166, v166
	v_exp_f32_e32 v167, v167
	v_exp_f32_e32 v165, v165
	v_cndmask_b32_e64 v81, 0, v81, s[40:41]
	v_cndmask_b32_e64 v168, 0, v164, s[22:23]
	v_cndmask_b32_e64 v166, 0, v166, s[34:35]
	v_cndmask_b32_e64 v167, 0, v167, s[18:19]
	v_cndmask_b32_e64 v169, 0, v165, s[28:29]
	v_cvt_pk_bf16_f32 v164, v174, v81
	v_cvt_pk_bf16_f32 v165, v175, v181
	v_cvt_pk_bf16_f32 v166, v168, v166
	v_cvt_pk_bf16_f32 v167, v167, v169
	v_mov_b32_e32 v181, v210
	v_mov_b32_e32 v208, v188
	v_mfma_f32_32x32x16_bf16 v[48:63], v[146:149], v[164:167], v[48:63]
	v_add_f32_e64 v146, v180, v208
	v_add_f32_e64 v147, v181, v209
	v_mov_b32_e32 v177, v242
	v_add_f32_e32 v81, v146, v147
	v_mul_f32_e32 v81, 0x3fb8aa3b, v81
	v_exp_f32_e32 v81, v81
	v_cndmask_b32_e32 v146, 0, v239, vcc
	v_cndmask_b32_e64 v81, 0, v81, s[36:37]
	v_mfma_f32_32x32x16_bf16 v[32:47], v[142:145], v[164:167], v[32:47]
	v_add_f32_e32 v143, v180, v190
	v_add_f32_e32 v144, v180, v189
	v_add_f32_e32 v143, v143, v209
	v_mul_f32_e32 v143, 0x3fb8aa3b, v143
	v_exp_f32_e32 v143, v143
	v_cndmask_b32_e64 v142, 0, v241, s[16:17]
	v_mfma_f32_32x32x16_bf16 v[16:31], v[138:141], v[164:167], v[16:31]
	v_add_f32_e32 v139, v180, v191
	v_add_f32_e32 v138, v144, v211
	v_add_f32_e32 v139, 0, v139
	v_mul_f32_e32 v138, 0x3fb8aa3b, v138
	v_mul_f32_e32 v139, 0x3fb8aa3b, v139
	v_exp_f32_e32 v138, v138
	v_exp_f32_e32 v139, v139
	v_mfma_f32_32x32x16_bf16 v[0:15], v[134:137], v[164:167], v[0:15]
	v_cndmask_b32_e64 v136, 0, v143, s[24:25]
	v_cndmask_b32_e64 v137, 0, v138, s[14:15]
	v_cndmask_b32_e64 v138, 0, v139, s[20:21]
	v_cvt_pk_bf16_f32 v134, v213, v215
	v_cvt_pk_bf16_f32 v135, v146, v142
	v_cvt_pk_bf16_f32 v136, v81, v136
	v_cvt_pk_bf16_f32 v137, v137, v138
	ds_read_b64_tr_b16 v[138:139], v207 offset:50240
	ds_read_b64_tr_b16 v[142:143], v207 offset:50304
	ds_read_b64_tr_b16 v[146:147], v207 offset:50368
	ds_read_b64_tr_b16 v[140:141], v207 offset:52800
	ds_read_b64_tr_b16 v[144:145], v207 offset:52864
	ds_read_b64_tr_b16 v[148:149], v207 offset:52928
	v_mfma_f32_32x32x16_bf16 v[48:63], v[130:133], v[134:137], v[48:63]
	v_mov_b32_e32 v130, v64
	v_mov_b32_e32 v131, v68
	v_mul_f32_e64 v132, v130, s68
	v_mul_f32_e64 v133, v131, s68
	v_mov_b32_e32 v81, v172
	v_mul_f32_e64 v64, |v132|, s54
	v_exp_f32_e32 v64, v64
	v_pk_add_f32 v[80:81], v[80:81], v[176:177]
	s_waitcnt lgkmcnt(2)
	v_mfma_f32_32x32x16_bf16 v[32:47], v[138:141], v[134:137], v[32:47]
	v_add_f32_e64 v80, v80, v182
	v_add_f32_e64 v81, v81, v183
	v_add_f32_e32 v64, 1.0, v64
	s_nop 1
	v_log_f32_e32 v138, v64
	v_min_f32_e32 v64, 0, v132
	s_waitcnt lgkmcnt(1)
	v_mfma_f32_32x32x16_bf16 v[16:31], v[142:145], v[134:137], v[16:31]
	v_mul_f32_e64 v143, |v133|, s54
	v_mul_f32_e32 v68, 0x3f317217, v138
	v_fma_f32 v132, v138, s86, -v68
	v_mov_b32_e32 v68, v65
	v_fmac_f32_e32 v132, 0x3377d1cf, v138
	v_fmac_f32_e32 v132, 0x3f317217, v138
	s_waitcnt lgkmcnt(0)
	v_mfma_f32_32x32x16_bf16 v[0:15], v[146:149], v[134:137], v[0:15]
	v_mul_f32_e64 v134, v68, s68
	v_mul_f32_e64 v135, v69, s68
	v_mul_f32_e64 v65, |v134|, s54
	v_exp_f32_e32 v65, v65
	v_mov_b32_e32 v137, v70
	v_exp_f32_e32 v143, v143
	v_min_f32_e32 v134, 0, v134
	v_add_f32_e32 v65, 1.0, v65
	v_add_f32_e32 v143, 1.0, v143
	s_nop 0
	v_log_f32_e32 v65, v65
	s_nop 0
	v_mul_f32_e32 v136, 0x3f317217, v65
	v_fma_f32 v140, v65, s86, -v136
	v_mov_b32_e32 v136, v66
	v_pk_mul_f32 v[138:139], v[136:137], s[68:69] op_sel_hi:[1,0]
	v_fmac_f32_e32 v140, 0x3377d1cf, v65
	v_mul_f32_e64 v66, |v138|, s54
	v_exp_f32_e32 v66, v66
	v_fmac_f32_e32 v140, 0x3f317217, v65
	v_min_f32_e32 v138, 0, v138
	v_add_f32_e32 v66, 1.0, v66
	v_mov_b32_e32 v65, v140
	s_nop 1
	v_log_f32_e32 v142, v66
	v_mov_b32_e32 v70, v67
	v_pk_mul_f32 v[140:141], v[70:71], s[68:69] op_sel_hi:[1,0]
	v_mul_f32_e64 v67, |v140|, s54
	v_exp_f32_e32 v67, v67
	v_mov_b32_e32 v66, v65
	v_mul_f32_e32 v65, 0x3f317217, v142
	v_fma_f32 v65, v142, s86, -v65
	v_fmac_f32_e32 v65, 0x3377d1cf, v142
	v_fmac_f32_e32 v65, 0x3f317217, v142
	v_add_f32_e32 v67, 1.0, v67
	v_min_f32_e32 v140, 0, v140
	s_nop 1
	v_log_f32_e32 v67, v67
	v_mov_b32_e32 v142, v65
	v_mul_f32_e32 v65, 0x3f317217, v67
	v_fma_f32 v65, v67, s86, -v65
	v_fmac_f32_e32 v65, 0x3377d1cf, v67
	v_fmac_f32_e32 v65, 0x3f317217, v67
	s_nop 1
	s_nop 0
	v_log_f32_e32 v143, v143
	v_mov_b32_e32 v144, v65
	v_min_f32_e32 v65, 0, v133
	v_or_b32_e32 v67, 8, v163
	v_mul_f32_e32 v133, 0x3f317217, v143
	v_fma_f32 v133, v143, s86, -v133
	v_fmac_f32_e32 v133, 0x3377d1cf, v143
	v_fmac_f32_e32 v133, 0x3f317217, v143
	s_nop 1
	v_pk_add_f32 v[64:65], v[64:65], v[132:133] neg_lo:[0,1] neg_hi:[0,1]
	v_mul_f32_e64 v132, |v135|, s54
	v_exp_f32_e32 v132, v132
	v_cmp_lt_i32_e32 vcc, v67, v153
	v_pk_fma_f32 v[130:131], v[130:131], s[68:69], v[64:65] op_sel_hi:[1,0,1] neg_lo:[1,0,0] neg_hi:[1,0,0]
	v_cmp_lt_i32_e64 s[14:15], v163, v152
	v_add_f32_e32 v67, 1.0, v132
	s_nop 0
	v_cndmask_b32_e64 v146, 0, v130, s[14:15]
	v_min_f32_e32 v135, 0, v135
	v_log_f32_e32 v67, v67
	v_cndmask_b32_e32 v147, 0, v131, vcc
	v_or_b32_e32 v131, 1, v163
	v_or_b32_e32 v130, 9, v163
	v_mul_f32_e32 v132, 0x3f317217, v67
	v_fma_f32 v132, v67, s86, -v132
	v_fmac_f32_e32 v132, 0x3377d1cf, v67
	v_fmac_f32_e32 v132, 0x3f317217, v67
	s_nop 1
	v_mov_b32_e32 v67, v132
	v_mov_b32_e32 v67, v67
	v_mul_f32_e64 v132, |v139|, s54
	v_pk_add_f32 v[66:67], v[134:135], v[66:67] neg_lo:[0,1] neg_hi:[0,1]
	v_exp_f32_e32 v134, v132
	v_pk_fma_f32 v[68:69], v[68:69], s[68:69], v[66:67] op_sel_hi:[1,0,1] neg_lo:[1,0,0] neg_hi:[1,0,0]
	v_cmp_lt_i32_e64 s[18:19], v131, v152
	v_cmp_lt_i32_e64 s[16:17], v130, v153
	v_min_f32_e32 v139, 0, v139
	v_cndmask_b32_e64 v132, 0, v68, s[18:19]
	v_add_f32_e32 v68, 1.0, v134
	v_cndmask_b32_e64 v133, 0, v69, s[16:17]
	v_or_b32_e32 v135, 2, v163
	v_log_f32_e32 v68, v68
	v_cmp_lt_i32_e64 s[24:25], v135, v152
	v_or_b32_e32 v134, 10, v163
	v_mul_f32_e32 v69, 0x3f317217, v68
	v_fma_f32 v69, v68, s86, -v69
	v_fmac_f32_e32 v69, 0x3377d1cf, v68
	v_fmac_f32_e32 v69, 0x3f317217, v68
	s_nop 1
	v_mov_b32_e32 v68, v69
	v_mov_b32_e32 v143, v68
	v_pk_add_f32 v[68:69], v[138:139], v[142:143] neg_lo:[0,1] neg_hi:[0,1]
	v_cmp_lt_i32_e64 s[22:23], v134, v153
	v_pk_fma_f32 v[130:131], v[136:137], s[68:69], v[68:69] op_sel_hi:[1,0,1] neg_lo:[1,0,0] neg_hi:[1,0,0]
	v_mul_f32_e64 v136, |v141|, s54
	v_exp_f32_e32 v136, v136
	v_cndmask_b32_e64 v142, 0, v130, s[24:25]
	v_cndmask_b32_e64 v143, 0, v131, s[22:23]
	v_pk_mul_f32 v[134:135], v[72:73], s[68:69] op_sel_hi:[1,0]
	v_add_f32_e32 v130, 1.0, v136
	v_mul_f32_e64 v138, |v134|, s54
	v_exp_f32_e32 v138, v138
	v_log_f32_e32 v130, v130
	v_or_b32_e32 v136, 11, v163
	v_or_b32_e32 v137, 3, v163
	v_cmp_lt_i32_e64 s[34:35], v137, v152
	v_mul_f32_e32 v131, 0x3f317217, v130
	v_fma_f32 v131, v130, s86, -v131
	v_fmac_f32_e32 v131, 0x3377d1cf, v130
	v_fmac_f32_e32 v131, 0x3f317217, v130
	v_min_f32_e32 v134, 0, v134
	v_min_f32_e32 v141, 0, v141
	v_mov_b32_e32 v130, v131
	v_cmp_lt_i32_e64 s[26:27], v136, v153
	v_add_f32_e32 v136, 1.0, v138
	v_mov_b32_e32 v145, v130
	v_pk_add_f32 v[130:131], v[140:141], v[144:145] neg_lo:[0,1] neg_hi:[0,1]
	v_log_f32_e32 v136, v136
	v_mul_f32_e64 v138, |v135|, s54
	v_exp_f32_e32 v138, v138
	v_min_f32_e32 v135, 0, v135
	v_mul_f32_e32 v137, 0x3f317217, v136
	v_fma_f32 v137, v136, s86, -v137
	v_fmac_f32_e32 v137, 0x3377d1cf, v136
	v_fmac_f32_e32 v137, 0x3f317217, v136
	v_or_b32_e32 v140, 16, v163
	v_cmp_lt_i32_e64 s[36:37], v140, v152
	v_mov_b32_e32 v136, v137
	v_add_f32_e32 v137, 1.0, v138
	v_pk_fma_f32 v[70:71], v[70:71], s[68:69], v[130:131] op_sel_hi:[1,0,1] neg_lo:[1,0,0] neg_hi:[1,0,0]
	s_nop 0
	v_log_f32_e32 v137, v137
	v_mov_b32_e32 v136, v136
	v_cndmask_b32_e64 v71, 0, v71, s[26:27]
	v_mul_f32_e32 v138, 0x3f317217, v137
	v_fma_f32 v138, v137, s86, -v138
	v_fmac_f32_e32 v138, 0x3377d1cf, v137
	v_fmac_f32_e32 v138, 0x3f317217, v137
	v_cndmask_b32_e64 v70, 0, v70, s[34:35]
	s_nop 0
	v_mov_b32_e32 v137, v138
	v_mov_b32_e32 v137, v137
	v_pk_add_f32 v[134:135], v[134:135], v[136:137] neg_lo:[0,1] neg_hi:[0,1]
	v_pk_mul_f32 v[136:137], v[74:75], s[68:69] op_sel_hi:[1,0]
	v_or_b32_e32 v138, 17, v163
	v_mul_f32_e64 v139, |v136|, s54
	v_exp_f32_e32 v139, v139
	v_cmp_lt_i32_e64 s[20:21], v138, v153
	v_mul_f32_e64 v140, |v137|, s54
	v_exp_f32_e32 v140, v140
	v_add_f32_e32 v138, 1.0, v139
	v_min_f32_e32 v136, 0, v136
	v_min_f32_e32 v137, 0, v137
	v_log_f32_e32 v138, v138
	v_pk_fma_f32 v[72:73], v[72:73], s[68:69], v[134:135] op_sel_hi:[1,0,1] neg_lo:[1,0,0] neg_hi:[1,0,0]
	v_mul_f32_e32 v139, 0x3f317217, v138
	v_fma_f32 v139, v138, s86, -v139
	v_fmac_f32_e32 v139, 0x3377d1cf, v138
	v_fmac_f32_e32 v139, 0x3f317217, v138
	v_cndmask_b32_e64 v73, 0, v73, s[20:21]
	v_cndmask_b32_e64 v72, 0, v72, s[36:37]
	v_mov_b32_e32 v138, v139
	v_add_f32_e32 v139, 1.0, v140
	s_nop 1
	v_log_f32_e32 v139, v139
	v_mov_b32_e32 v138, v138
	v_mul_f32_e32 v140, 0x3f317217, v139
	v_fma_f32 v140, v139, s86, -v140
	v_fmac_f32_e32 v140, 0x3377d1cf, v139
	v_fmac_f32_e32 v140, 0x3f317217, v139
	s_nop 1
	v_mov_b32_e32 v139, v140
	v_mov_b32_e32 v139, v139
	v_or_b32_e32 v140, 18, v163
	v_cmp_lt_i32_e64 s[30:31], v140, v152
	v_pk_add_f32 v[140:141], v[142:143], v[70:71]
	v_mov_b32_e32 v142, v76
	v_mov_b32_e32 v143, v78
	v_pk_mul_f32 v[144:145], v[142:143], s[68:69] op_sel_hi:[1,0]
	v_pk_add_f32 v[136:137], v[136:137], v[138:139] neg_lo:[0,1] neg_hi:[0,1]
	v_mul_f32_e64 v76, |v144|, s54
	v_exp_f32_e32 v78, v76
	v_or_b32_e32 v138, 19, v163
	v_pk_fma_f32 v[74:75], v[74:75], s[68:69], v[136:137] op_sel_hi:[1,0,1] neg_lo:[1,0,0] neg_hi:[1,0,0]
	v_cmp_lt_i32_e64 s[28:29], v138, v153
	v_cndmask_b32_e64 v138, 0, v74, s[30:31]
	v_mul_f32_e64 v149, |v145|, s54
	v_cndmask_b32_e64 v139, 0, v75, s[28:29]
	v_pk_add_f32 v[74:75], v[146:147], v[132:133]
	v_exp_f32_e32 v149, v149
	v_pk_add_f32 v[146:147], v[74:75], v[140:141]
	v_add_f32_e32 v74, 1.0, v78
	ds_bpermute_b32 v148, v235, v147
	ds_bpermute_b32 v76, v235, v146
	v_log_f32_e32 v75, v74
	v_mov_b32_e32 v74, v73
	v_mul_f32_e32 v78, 0x3f317217, v75
	v_pk_add_f32 v[164:165], v[72:73], v[74:75]
	v_min_f32_e32 v74, 0, v144
	v_fma_f32 v144, v75, s86, -v78
	v_mov_b32_e32 v78, v77
	v_pk_mul_f32 v[166:167], v[78:79], s[68:69] op_sel_hi:[1,0]
	v_fmac_f32_e32 v144, 0x3377d1cf, v75
	v_mul_f32_e64 v77, |v166|, s54
	v_exp_f32_e32 v77, v77
	v_fmac_f32_e32 v144, 0x3f317217, v75
	v_min_f32_e32 v166, 0, v166
	v_add_f32_e32 v77, 1.0, v77
	v_mov_b32_e32 v75, v144
	v_or_b32_e32 v165, 24, v163
	v_cmp_lt_i32_e64 s[42:43], v165, v152
	v_log_f32_e32 v77, v77
	v_mov_b32_e32 v144, v75
	v_mul_f32_e32 v75, 0x3f317217, v77
	v_fma_f32 v75, v77, s86, -v75
	v_fmac_f32_e32 v75, 0x3377d1cf, v77
	v_fmac_f32_e32 v75, 0x3f317217, v77
	s_nop 1
	v_mov_b32_e32 v168, v75
	v_add_f32_e32 v75, 1.0, v149
	v_or_b32_e32 v149, 26, v163
	s_nop 0
	v_log_f32_e32 v77, v75
	v_min_f32_e32 v75, 0, v145
	v_mul_f32_e32 v145, 0x3f317217, v77
	v_fma_f32 v145, v77, s86, -v145
	v_fmac_f32_e32 v145, 0x3377d1cf, v77
	v_fmac_f32_e32 v145, 0x3f317217, v77
	s_nop 1
	v_mov_b32_e32 v77, v145
	v_mov_b32_e32 v145, v77
	v_mul_f32_e64 v77, |v167|, s54
	v_exp_f32_e32 v77, v77
	v_pk_add_f32 v[74:75], v[74:75], v[144:145] neg_lo:[0,1] neg_hi:[0,1]
	v_min_f32_e32 v167, 0, v167
	v_cmp_lt_i32_e64 s[38:39], v149, v153
	v_add_f32_e32 v77, 1.0, v77
	v_or_b32_e32 v149, 27, v163
	v_or_b32_e32 v163, 25, v163
	v_log_f32_e32 v77, v77
	v_pk_fma_f32 v[142:143], v[142:143], s[68:69], v[74:75] op_sel_hi:[1,0,1] neg_lo:[1,0,0] neg_hi:[1,0,0]
	v_mul_f32_e32 v144, 0x3f317217, v77
	v_fma_f32 v144, v77, s86, -v144
	v_fmac_f32_e32 v144, 0x3377d1cf, v77
	v_fmac_f32_e32 v144, 0x3f317217, v77
	v_cndmask_b32_e64 v143, 0, v143, s[38:39]
	v_cndmask_b32_e64 v142, 0, v142, s[42:43]
	v_mov_b32_e32 v77, v144
	v_mov_b32_e32 v169, v77
	v_pk_add_f32 v[144:145], v[166:167], v[168:169] neg_lo:[0,1] neg_hi:[0,1]
	v_cmp_lt_i32_e64 s[40:41], v149, v153
	v_pk_fma_f32 v[78:79], v[78:79], s[68:69], v[144:145] op_sel_hi:[1,0,1] neg_lo:[1,0,0] neg_hi:[1,0,0]
	v_cmp_lt_i32_e64 s[44:45], v163, v152
	v_cndmask_b32_e64 v167, 0, v79, s[40:41]
	v_mov_b32_e32 v168, v132
	v_cndmask_b32_e64 v166, 0, v78, s[44:45]
	v_mov_b32_e32 v132, v139
	v_pk_add_f32 v[142:143], v[142:143], v[166:167]
	v_pk_add_f32 v[170:171], v[138:139], v[132:133]
	v_mov_b32_e32 v165, v142
	v_mov_b32_e32 v171, v143
	v_pk_add_f32 v[164:165], v[164:165], v[170:171]
	ds_bpermute_b32 v149, v235, v165
	ds_bpermute_b32 v77, v235, v164
	v_pk_add_f32 v[78:79], v[146:147], v[146:147] op_sel_hi:[0,1]
	v_mov_b32_e32 v169, v64
	v_mov_b32_e32 v64, v133
	v_pk_add_f32 v[132:133], v[164:165], v[164:165] op_sel:[0,1] op_sel_hi:[1,0]
	s_waitcnt lgkmcnt(1)
	v_add_f32_e32 v142, v165, v149
	s_waitcnt lgkmcnt(0)
	v_cndmask_b32_e64 v146, 0, v77, s[10:11]
	v_add_f32_e32 v142, v146, v142
	v_add_f32_e32 v146, v132, v149
	v_add_f32_e32 v147, v147, v132
	v_add_f32_e32 v146, v146, v77
	v_cndmask_b32_e64 v163, 0, v148, s[10:11]
	v_add_f32_e32 v147, v147, v149
	v_add_f32_e32 v146, v163, v146
	v_add_f32_e32 v147, v147, v77
	v_cndmask_b32_e64 v163, 0, v76, s[10:11]
	v_pk_add_f32 v[76:77], v[76:77], v[148:149]
	v_mov_b32_e32 v78, v80
	v_add_f32_e32 v147, v147, v148
	v_pk_add_f32 v[76:77], v[76:77], v[76:77] op_sel_hi:[0,1]
	v_pk_mov_b32 v[80:81], v[80:81], v[132:133] op_sel:[1,0]
	v_add_f32_e32 v147, v163, v147
	v_pk_add_f32 v[78:79], v[78:79], v[80:81]
	v_mov_b32_e32 v163, v77
	v_pk_add_f32 v[80:81], v[162:163], v[78:79]
	v_mov_b32_e32 v76, v140
	v_add_f32_e32 v77, v80, v147
	v_pk_add_f32 v[78:79], v[168:169], v[76:77]
	v_add_f32_e32 v68, v68, v77
	v_add_f32_e32 v76, v78, v79
	v_mul_f32_e32 v76, 0x3fb8aa3b, v76
	v_exp_f32_e32 v76, v76
	v_add_f32_e32 v66, v66, v77
	v_add_f32_e32 v68, v70, v68
	v_add_f32_e32 v70, v130, v77
	v_cndmask_b32_e64 v78, 0, v76, s[14:15]
	v_add_f32_e32 v77, v80, v146
	v_mov_b32_e32 v76, v141
	v_add_f32_e32 v66, v140, v66
	v_pk_add_f32 v[64:65], v[64:65], v[76:77]
	v_mul_f32_e32 v66, 0x3fb8aa3b, v66
	v_add_f32_e32 v64, v64, v65
	v_add_f32_e32 v65, v67, v77
	v_exp_f32_e32 v66, v66
	v_add_f32_e32 v65, v141, v65
	v_mul_f32_e32 v64, 0x3fb8aa3b, v64
	v_mul_f32_e32 v65, 0x3fb8aa3b, v65
	v_exp_f32_e32 v64, v64
	v_exp_f32_e32 v65, v65
	v_cndmask_b32_e64 v79, 0, v66, s[18:19]
	v_add_f32_e32 v66, v69, v77
	v_add_f32_e32 v66, v71, v66
	v_mul_f32_e32 v66, 0x3fb8aa3b, v66
	v_cndmask_b32_e32 v71, 0, v64, vcc
	v_cndmask_b32_e64 v76, 0, v65, s[16:17]
	v_add_f32_e32 v171, v80, v142
	v_pk_mov_b32 v[64:65], v[72:73], v[134:135] op_sel:[1,0]
	v_exp_f32_e32 v66, v66
	v_add_f32_e32 v67, v131, v77
	v_pk_add_f32 v[64:65], v[64:65], v[170:171]
	v_add_f32_e32 v67, 0, v67
	v_add_f32_e32 v64, v64, v65
	v_add_f32_e32 v65, v135, v171
	v_mul_f32_e32 v67, 0x3fb8aa3b, v67
	v_mul_f32_e32 v64, 0x3fb8aa3b, v64
	v_add_f32_e32 v65, v170, v65
	v_exp_f32_e32 v67, v67
	v_exp_f32_e32 v64, v64
	v_mul_f32_e32 v65, 0x3fb8aa3b, v65
	v_add_f32_e32 v70, 0, v70
	v_cndmask_b32_e64 v77, 0, v66, s[22:23]
	v_exp_f32_e32 v140, v65
	v_add_f32_e32 v65, v136, v171
	v_add_f32_e32 v66, v137, v171
	v_mul_f32_e32 v68, 0x3fb8aa3b, v68
	v_mul_f32_e32 v70, 0x3fb8aa3b, v70
	v_add_f32_e32 v65, v139, v65
	v_add_f32_e32 v66, 0, v66
	v_exp_f32_e32 v68, v68
	v_exp_f32_e32 v70, v70
	v_mul_f32_e32 v65, 0x3fb8aa3b, v65
	v_mul_f32_e32 v66, 0x3fb8aa3b, v66
	v_cndmask_b32_e64 v131, 0, v67, s[26:27]
	v_exp_f32_e32 v139, v66
	v_exp_f32_e32 v141, v65
	v_cndmask_b32_e64 v146, 0, v64, s[36:37]
	ds_read_b64_tr_b16 v[64:65], v207 offset:34816
	ds_read_b64_tr_b16 v[66:67], v207 offset:37376
	v_cndmask_b32_e64 v138, 0, v149, s[10:11]
	v_add_f32_e32 v72, v80, v138
	v_mov_b32_e32 v73, v166
	v_mov_b32_e32 v142, v74
	v_cndmask_b32_e64 v130, 0, v68, s[24:25]
	v_cndmask_b32_e64 v70, 0, v70, s[34:35]
	v_pk_add_f32 v[68:69], v[72:73], v[142:143]
	v_cndmask_b32_e64 v74, 0, v139, s[28:29]
	v_add_f32_e32 v73, v68, v69
	v_cvt_pk_bf16_f32 v68, v78, v79
	v_cvt_pk_bf16_f32 v69, v130, v70
	v_cvt_pk_bf16_f32 v70, v71, v76
	v_cvt_pk_bf16_f32 v71, v77, v131
	ds_read_b64_tr_b16 v[76:77], v207 offset:34880
	ds_read_b64_tr_b16 v[130:131], v207 offset:34944
	ds_read_b64_tr_b16 v[134:135], v207 offset:35008
	ds_read_b64_tr_b16 v[78:79], v207 offset:37440
	ds_read_b64_tr_b16 v[132:133], v207 offset:37504
	ds_read_b64_tr_b16 v[136:137], v207 offset:37568
	s_waitcnt lgkmcnt(6)
	v_mfma_f32_32x32x16_bf16 v[48:63], v[64:67], v[68:71], v[48:63]
	v_mul_f32_e32 v64, 0x3fb8aa3b, v73
	v_exp_f32_e32 v64, v64
	v_add_f32_e32 v65, v72, v75
	v_add_f32_e32 v65, v65, v167
	v_mul_f32_e32 v65, 0x3fb8aa3b, v65
	v_cndmask_b32_e64 v139, 0, v64, s[42:43]
	v_add_f32_e32 v64, v72, v144
	v_exp_f32_e32 v75, v65
	v_add_f32_e32 v65, v72, v145
	v_add_f32_e32 v64, v64, v143
	v_add_f32_e32 v65, 0, v65
	v_mul_f32_e32 v64, 0x3fb8aa3b, v64
	v_mul_f32_e32 v65, 0x3fb8aa3b, v65
	v_exp_f32_e32 v64, v64
	v_exp_f32_e32 v72, v65
	s_waitcnt lgkmcnt(2)
	v_mfma_f32_32x32x16_bf16 v[32:47], v[76:79], v[68:71], v[32:47]
	v_cndmask_b32_e64 v73, 0, v140, s[20:21]
	v_cndmask_b32_e64 v138, 0, v141, s[30:31]
	v_cndmask_b32_e64 v76, 0, v64, s[44:45]
	v_cndmask_b32_e64 v72, 0, v72, s[40:41]
	ds_read_b64_tr_b16 v[64:65], v207 offset:39936
	ds_read_b64_tr_b16 v[66:67], v207 offset:42496
	v_add_f32_e32 v162, v80, v81
	s_mov_b32 s14, 0xc2480000
	s_waitcnt lgkmcnt(3)
	v_mfma_f32_32x32x16_bf16 v[16:31], v[130:133], v[68:71], v[16:31]
	v_cmp_gt_f32_e32 vcc, s14, v162
	s_cmp_eq_u64 vcc, exec
	s_cselect_b64 s[14:15], -1, 0
	s_waitcnt lgkmcnt(2)
	v_mfma_f32_32x32x16_bf16 v[0:15], v[134:137], v[68:71], v[0:15]
	v_cndmask_b32_e64 v71, 0, v75, s[38:39]
	v_cvt_pk_bf16_f32 v68, v146, v73
	v_cvt_pk_bf16_f32 v69, v138, v74
	v_cvt_pk_bf16_f32 v70, v139, v76
	v_cvt_pk_bf16_f32 v71, v71, v72
	ds_read_b64_tr_b16 v[72:73], v207 offset:40000
	ds_read_b64_tr_b16 v[76:77], v207 offset:40064
	ds_read_b64_tr_b16 v[130:131], v207 offset:40128
	ds_read_b64_tr_b16 v[74:75], v207 offset:42560
	ds_read_b64_tr_b16 v[78:79], v207 offset:42624
	ds_read_b64_tr_b16 v[132:133], v207 offset:42688
	s_waitcnt lgkmcnt(6)
	v_mfma_f32_32x32x16_bf16 v[48:63], v[64:67], v[68:71], v[48:63]
	s_waitcnt lgkmcnt(2)
	v_mfma_f32_32x32x16_bf16 v[32:47], v[72:75], v[68:71], v[32:47]
	s_waitcnt lgkmcnt(1)
	v_mfma_f32_32x32x16_bf16 v[16:31], v[76:79], v[68:71], v[16:31]
	s_waitcnt lgkmcnt(0)
	v_mfma_f32_32x32x16_bf16 v[0:15], v[130:133], v[68:71], v[0:15]
